# UP GEMM: first K-tile MFMAs take srcC=0 (no 128 v_mov accumulator zeroing per unit)
# baseline (speedup 1.0000x reference)
.LBB0_564:
	s_ashr_i32 s21, s20, 31
	s_lshl_b64 s[22:23], s[20:21], 19
	s_add_u32 s22, s14, s22
	s_addc_u32 s23, s15, s23
	s_and_b64 s[30:31], s[36:37], exec
	s_cselect_b32 s21, s23, s41
	s_cselect_b32 s47, s22, s40
	s_ashr_i32 s19, s18, 31
	s_lshl_b64 s[30:31], s[18:19], 19
	s_add_u32 s30, s2, s30
	s_addc_u32 s31, s3, s31
	s_and_b64 s[42:43], s[36:37], exec
	s_cselect_b32 s19, s31, s39
	s_cselect_b32 s48, s30, s38
	s_add_u32 s49, s38, 0x100
	s_addc_u32 s50, s39, 0
	s_add_u32 s38, s40, 0x40080
	s_addc_u32 s39, s41, 0
	s_mov_b32 s51, -2
.LBB0_565:
	s_add_u32 s40, s38, 0xfffc0080
	s_addc_u32 s41, s39, -1
	s_add_i32 s52, 0, 0x10000
	s_cmp_eq_u32 s51, 12
	s_cselect_b32 s43, s21, s41
	s_cselect_b32 s42, s47, s40
	v_add_u32_e32 v0, s52, v141
	s_cselect_b32 s41, s19, s50
	s_cselect_b32 s40, s48, s49
	s_add_i32 s54, 0, 0x14000
	ds_read_b128 v[146:149], v0
	ds_read_b128 v[150:153], v0 offset:1024
	ds_read_b128 v[154:157], v0 offset:2048
	ds_read_b128 v[158:161], v0 offset:3072
	v_add_u32_e32 v0, s54, v141
	ds_read_b128 v[162:165], v0
	ds_read_b128 v[166:169], v0 offset:1024
	ds_read_b128 v[170:173], v0 offset:2048
	ds_read_b128 v[174:177], v0 offset:3072
	s_add_i32 m0, s8, 0xc000
	ds_read_b128 v[178:181], v145
	ds_read_b128 v[182:185], v145 offset:1024
	ds_read_b128 v[186:189], v145 offset:2048
	ds_read_b128 v[190:193], v145 offset:3072
	ds_read_b128 v[194:197], v145 offset:4096
	ds_read_b128 v[208:211], v145 offset:5120
	ds_read_b128 v[212:215], v145 offset:6144
	ds_read_b128 v[216:219], v145 offset:7168
	global_load_lds_dwordx4 v138, s[38:39]
	s_add_i32 m0, s8, 0xe000
	s_nop 0
	global_load_lds_dwordx4 v136, s[38:39]
	s_waitcnt vmcnt(8)
	s_waitcnt lgkmcnt(0)
	s_barrier
	s_setprio 1
	s_waitcnt lgkmcnt(0)
	s_cmp_lg_u32 s51, -2
	s_cbranch_scc1 .Lc0n_up_0
	v_mfma_f32_16x16x32_bf16 v[130:133], v[146:149], v[178:181], 0
	v_mfma_f32_16x16x32_bf16 v[126:129], v[154:157], v[178:181], 0
	v_mfma_f32_16x16x32_bf16 v[114:117], v[146:149], v[186:189], 0
	v_mfma_f32_16x16x32_bf16 v[110:113], v[154:157], v[186:189], 0
	v_mfma_f32_16x16x32_bf16 v[98:101], v[146:149], v[194:197], 0
	v_mfma_f32_16x16x32_bf16 v[90:93], v[154:157], v[194:197], 0
	v_mfma_f32_16x16x32_bf16 v[78:81], v[146:149], v[212:215], 0
	v_mfma_f32_16x16x32_bf16 v[74:77], v[154:157], v[212:215], 0
	s_branch .Lc0d_up_0
.Lc0n_up_0:
	v_mfma_f32_16x16x32_bf16 v[130:133], v[146:149], v[178:181], v[130:133]
	v_mfma_f32_16x16x32_bf16 v[126:129], v[154:157], v[178:181], v[126:129]
	v_mfma_f32_16x16x32_bf16 v[114:117], v[146:149], v[186:189], v[114:117]
	v_mfma_f32_16x16x32_bf16 v[110:113], v[154:157], v[186:189], v[110:113]
	v_mfma_f32_16x16x32_bf16 v[98:101], v[146:149], v[194:197], v[98:101]
	v_mfma_f32_16x16x32_bf16 v[90:93], v[154:157], v[194:197], v[90:93]
	v_mfma_f32_16x16x32_bf16 v[78:81], v[146:149], v[212:215], v[78:81]
	v_mfma_f32_16x16x32_bf16 v[74:77], v[154:157], v[212:215], v[74:77]
.Lc0d_up_0:
	v_mfma_f32_16x16x32_bf16 v[130:133], v[150:153], v[182:185], v[130:133]
	v_mfma_f32_16x16x32_bf16 v[126:129], v[158:161], v[182:185], v[126:129]
	v_mfma_f32_16x16x32_bf16 v[114:117], v[150:153], v[190:193], v[114:117]
	v_mfma_f32_16x16x32_bf16 v[110:113], v[158:161], v[190:193], v[110:113]
	v_mfma_f32_16x16x32_bf16 v[98:101], v[150:153], v[208:211], v[98:101]
	v_mfma_f32_16x16x32_bf16 v[90:93], v[158:161], v[208:211], v[90:93]
	v_mfma_f32_16x16x32_bf16 v[78:81], v[150:153], v[216:219], v[78:81]
	v_mfma_f32_16x16x32_bf16 v[74:77], v[158:161], v[216:219], v[74:77]
	s_setprio 0
	s_setprio 1
	s_cmp_lg_u32 s51, -2
	s_cbranch_scc1 .Lc0n_up_1
	v_mfma_f32_16x16x32_bf16 v[122:125], v[162:165], v[178:181], 0
	v_mfma_f32_16x16x32_bf16 v[118:121], v[170:173], v[178:181], 0
	v_mfma_f32_16x16x32_bf16 v[106:109], v[162:165], v[186:189], 0
	v_mfma_f32_16x16x32_bf16 v[102:105], v[170:173], v[186:189], 0
	v_mfma_f32_16x16x32_bf16 v[86:89], v[162:165], v[194:197], 0
	v_mfma_f32_16x16x32_bf16 v[82:85], v[170:173], v[194:197], 0
	v_mfma_f32_16x16x32_bf16 v[70:73], v[162:165], v[212:215], 0
	v_mfma_f32_16x16x32_bf16 v[66:69], v[170:173], v[212:215], 0
	s_branch .Lc0d_up_1
.Lc0n_up_1:
	v_mfma_f32_16x16x32_bf16 v[122:125], v[162:165], v[178:181], v[122:125]
	v_mfma_f32_16x16x32_bf16 v[118:121], v[170:173], v[178:181], v[118:121]
	v_mfma_f32_16x16x32_bf16 v[106:109], v[162:165], v[186:189], v[106:109]
	v_mfma_f32_16x16x32_bf16 v[102:105], v[170:173], v[186:189], v[102:105]
	v_mfma_f32_16x16x32_bf16 v[86:89], v[162:165], v[194:197], v[86:89]
	v_mfma_f32_16x16x32_bf16 v[82:85], v[170:173], v[194:197], v[82:85]
	v_mfma_f32_16x16x32_bf16 v[70:73], v[162:165], v[212:215], v[70:73]
	v_mfma_f32_16x16x32_bf16 v[66:69], v[170:173], v[212:215], v[66:69]
.Lc0d_up_1:
	v_mfma_f32_16x16x32_bf16 v[122:125], v[166:169], v[182:185], v[122:125]
	v_mfma_f32_16x16x32_bf16 v[118:121], v[174:177], v[182:185], v[118:121]
	v_mfma_f32_16x16x32_bf16 v[106:109], v[166:169], v[190:193], v[106:109]
	v_mfma_f32_16x16x32_bf16 v[102:105], v[174:177], v[190:193], v[102:105]
	v_mfma_f32_16x16x32_bf16 v[86:89], v[166:169], v[208:211], v[86:89]
	v_mfma_f32_16x16x32_bf16 v[82:85], v[174:177], v[208:211], v[82:85]
	v_mfma_f32_16x16x32_bf16 v[70:73], v[166:169], v[216:219], v[70:73]
	v_mfma_f32_16x16x32_bf16 v[66:69], v[174:177], v[216:219], v[66:69]
	s_setprio 0
	s_barrier
	s_add_i32 s52, s52, s6
	s_mov_b32 m0, s52
	ds_read_b128 v[178:181], v145 offset:16384
	ds_read_b128 v[182:185], v145 offset:17408
	ds_read_b128 v[186:189], v145 offset:18432
	ds_read_b128 v[190:193], v145 offset:19456
	ds_read_b128 v[194:197], v145 offset:20480
	ds_read_b128 v[208:211], v145 offset:21504
	ds_read_b128 v[212:215], v145 offset:22528
	ds_read_b128 v[216:219], v145 offset:23552
	global_load_lds_dwordx4 v134, s[40:41]
	s_add_i32 m0, s52, 0x2000
	s_add_u32 s52, s40, 0x40000
	s_addc_u32 s53, s41, 0
	s_add_i32 s54, s54, s6
	global_load_lds_dwordx4 v94, s[40:41]
	s_mov_b32 m0, s54
	s_nop 0
	global_load_lds_dwordx4 v134, s[52:53]
	s_add_i32 m0, s54, 0x2000
	s_nop 0
	global_load_lds_dwordx4 v94, s[52:53]
	s_mov_b32 m0, s8
	s_nop 0
	global_load_lds_dwordx4 v134, s[42:43]
	s_mov_b32 m0, s9
	s_nop 0
	global_load_lds_dwordx4 v94, s[42:43]
	s_waitcnt vmcnt(8)
	s_waitcnt lgkmcnt(0)
	s_barrier
	s_setprio 1
	s_waitcnt lgkmcnt(0)
	s_cmp_lg_u32 s51, -2
	s_cbranch_scc1 .Lc0n_up_2
	v_mfma_f32_16x16x32_bf16 v[62:65], v[146:149], v[178:181], 0
	v_mfma_f32_16x16x32_bf16 v[58:61], v[154:157], v[178:181], 0
	v_mfma_f32_16x16x32_bf16 v[46:49], v[146:149], v[186:189], 0
	v_mfma_f32_16x16x32_bf16 v[42:45], v[154:157], v[186:189], 0
	v_mfma_f32_16x16x32_bf16 v[30:33], v[146:149], v[194:197], 0
	v_mfma_f32_16x16x32_bf16 v[26:29], v[154:157], v[194:197], 0
	v_mfma_f32_16x16x32_bf16 v[14:17], v[146:149], v[212:215], 0
	v_mfma_f32_16x16x32_bf16 v[10:13], v[154:157], v[212:215], 0
	s_branch .Lc0d_up_2
.Lc0n_up_2:
	v_mfma_f32_16x16x32_bf16 v[62:65], v[146:149], v[178:181], v[62:65]
	v_mfma_f32_16x16x32_bf16 v[58:61], v[154:157], v[178:181], v[58:61]
	v_mfma_f32_16x16x32_bf16 v[46:49], v[146:149], v[186:189], v[46:49]
	v_mfma_f32_16x16x32_bf16 v[42:45], v[154:157], v[186:189], v[42:45]
	v_mfma_f32_16x16x32_bf16 v[30:33], v[146:149], v[194:197], v[30:33]
	v_mfma_f32_16x16x32_bf16 v[26:29], v[154:157], v[194:197], v[26:29]
	v_mfma_f32_16x16x32_bf16 v[14:17], v[146:149], v[212:215], v[14:17]
	v_mfma_f32_16x16x32_bf16 v[10:13], v[154:157], v[212:215], v[10:13]
.Lc0d_up_2:
	v_mfma_f32_16x16x32_bf16 v[62:65], v[150:153], v[182:185], v[62:65]
	v_mfma_f32_16x16x32_bf16 v[58:61], v[158:161], v[182:185], v[58:61]
	v_mfma_f32_16x16x32_bf16 v[46:49], v[150:153], v[190:193], v[46:49]
	v_mfma_f32_16x16x32_bf16 v[42:45], v[158:161], v[190:193], v[42:45]
	v_mfma_f32_16x16x32_bf16 v[30:33], v[150:153], v[208:211], v[30:33]
	v_mfma_f32_16x16x32_bf16 v[26:29], v[158:161], v[208:211], v[26:29]
	v_mfma_f32_16x16x32_bf16 v[14:17], v[150:153], v[216:219], v[14:17]
	v_mfma_f32_16x16x32_bf16 v[10:13], v[158:161], v[216:219], v[10:13]
	s_setprio 0
	s_setprio 1
	s_cmp_lg_u32 s51, -2
	s_cbranch_scc1 .Lc0n_up_3
	v_mfma_f32_16x16x32_bf16 v[54:57], v[162:165], v[178:181], 0
	v_mfma_f32_16x16x32_bf16 v[50:53], v[170:173], v[178:181], 0
	v_mfma_f32_16x16x32_bf16 v[38:41], v[162:165], v[186:189], 0
	v_mfma_f32_16x16x32_bf16 v[34:37], v[170:173], v[186:189], 0
	v_mfma_f32_16x16x32_bf16 v[22:25], v[162:165], v[194:197], 0
	v_mfma_f32_16x16x32_bf16 v[18:21], v[170:173], v[194:197], 0
	v_mfma_f32_16x16x32_bf16 v[6:9], v[162:165], v[212:215], 0
	v_mfma_f32_16x16x32_bf16 v[2:5], v[170:173], v[212:215], 0
	s_branch .Lc0d_up_3
.Lc0n_up_3:
	v_mfma_f32_16x16x32_bf16 v[54:57], v[162:165], v[178:181], v[54:57]
	v_mfma_f32_16x16x32_bf16 v[50:53], v[170:173], v[178:181], v[50:53]
	v_mfma_f32_16x16x32_bf16 v[38:41], v[162:165], v[186:189], v[38:41]
	v_mfma_f32_16x16x32_bf16 v[34:37], v[170:173], v[186:189], v[34:37]
	v_mfma_f32_16x16x32_bf16 v[22:25], v[162:165], v[194:197], v[22:25]
	v_mfma_f32_16x16x32_bf16 v[18:21], v[170:173], v[194:197], v[18:21]
	v_mfma_f32_16x16x32_bf16 v[6:9], v[162:165], v[212:215], v[6:9]
	v_mfma_f32_16x16x32_bf16 v[2:5], v[170:173], v[212:215], v[2:5]
.Lc0d_up_3:
	v_mfma_f32_16x16x32_bf16 v[54:57], v[166:169], v[182:185], v[54:57]
	v_mfma_f32_16x16x32_bf16 v[50:53], v[174:177], v[182:185], v[50:53]
	v_mfma_f32_16x16x32_bf16 v[38:41], v[166:169], v[190:193], v[38:41]
	v_mfma_f32_16x16x32_bf16 v[34:37], v[174:177], v[190:193], v[34:37]
	v_mfma_f32_16x16x32_bf16 v[22:25], v[166:169], v[208:211], v[22:25]
	v_mfma_f32_16x16x32_bf16 v[18:21], v[174:177], v[208:211], v[18:21]
	v_mfma_f32_16x16x32_bf16 v[6:9], v[166:169], v[216:219], v[6:9]
	v_mfma_f32_16x16x32_bf16 v[2:5], v[174:177], v[216:219], v[2:5]
	s_setprio 0
	s_barrier
	s_add_i32 s52, 0, 0x18000
	v_add_u32_e32 v0, s52, v141
	s_add_i32 s53, 0, 0x1c000
	ds_read_b128 v[146:149], v0
	ds_read_b128 v[150:153], v0 offset:1024
	ds_read_b128 v[154:157], v0 offset:2048
	ds_read_b128 v[158:161], v0 offset:3072
	v_add_u32_e32 v0, s53, v141
	ds_read_b128 v[162:165], v0
	ds_read_b128 v[166:169], v0 offset:1024
	ds_read_b128 v[170:173], v0 offset:2048
	ds_read_b128 v[174:177], v0 offset:3072
	s_add_u32 s42, s42, 0x40000
	s_addc_u32 s43, s43, 0
	s_mov_b32 m0, s12
	ds_read_b128 v[178:181], v145 offset:32768
	ds_read_b128 v[182:185], v145 offset:33792
	ds_read_b128 v[186:189], v145 offset:34816
	ds_read_b128 v[190:193], v145 offset:35840
	ds_read_b128 v[194:197], v145 offset:36864
	ds_read_b128 v[208:211], v145 offset:37888
	ds_read_b128 v[212:215], v145 offset:38912
	ds_read_b128 v[216:219], v145 offset:39936
	global_load_lds_dwordx4 v134, s[42:43]
	s_mov_b32 m0, s13
	s_nop 0
	global_load_lds_dwordx4 v94, s[42:43]
	s_waitcnt vmcnt(8)
	s_waitcnt lgkmcnt(0)
	s_barrier
	s_setprio 1
	s_waitcnt lgkmcnt(0)
	v_mfma_f32_16x16x32_bf16 v[130:133], v[146:149], v[178:181], v[130:133]
	v_mfma_f32_16x16x32_bf16 v[126:129], v[154:157], v[178:181], v[126:129]
	v_mfma_f32_16x16x32_bf16 v[114:117], v[146:149], v[186:189], v[114:117]
	v_mfma_f32_16x16x32_bf16 v[110:113], v[154:157], v[186:189], v[110:113]
	v_mfma_f32_16x16x32_bf16 v[98:101], v[146:149], v[194:197], v[98:101]
	v_mfma_f32_16x16x32_bf16 v[90:93], v[154:157], v[194:197], v[90:93]
	v_mfma_f32_16x16x32_bf16 v[78:81], v[146:149], v[212:215], v[78:81]
	v_mfma_f32_16x16x32_bf16 v[74:77], v[154:157], v[212:215], v[74:77]
	v_mfma_f32_16x16x32_bf16 v[130:133], v[150:153], v[182:185], v[130:133]
	v_mfma_f32_16x16x32_bf16 v[126:129], v[158:161], v[182:185], v[126:129]
	v_mfma_f32_16x16x32_bf16 v[114:117], v[150:153], v[190:193], v[114:117]
	v_mfma_f32_16x16x32_bf16 v[110:113], v[158:161], v[190:193], v[110:113]
	v_mfma_f32_16x16x32_bf16 v[98:101], v[150:153], v[208:211], v[98:101]
	v_mfma_f32_16x16x32_bf16 v[90:93], v[158:161], v[208:211], v[90:93]
	v_mfma_f32_16x16x32_bf16 v[78:81], v[150:153], v[216:219], v[78:81]
	v_mfma_f32_16x16x32_bf16 v[74:77], v[158:161], v[216:219], v[74:77]
	s_setprio 0
	s_setprio 1
	v_mfma_f32_16x16x32_bf16 v[122:125], v[162:165], v[178:181], v[122:125]
	v_mfma_f32_16x16x32_bf16 v[118:121], v[170:173], v[178:181], v[118:121]
	v_mfma_f32_16x16x32_bf16 v[106:109], v[162:165], v[186:189], v[106:109]
	v_mfma_f32_16x16x32_bf16 v[102:105], v[170:173], v[186:189], v[102:105]
	v_mfma_f32_16x16x32_bf16 v[86:89], v[162:165], v[194:197], v[86:89]
	v_mfma_f32_16x16x32_bf16 v[82:85], v[170:173], v[194:197], v[82:85]
	v_mfma_f32_16x16x32_bf16 v[70:73], v[162:165], v[212:215], v[70:73]
	v_mfma_f32_16x16x32_bf16 v[66:69], v[170:173], v[212:215], v[66:69]
	v_mfma_f32_16x16x32_bf16 v[122:125], v[166:169], v[182:185], v[122:125]
	v_mfma_f32_16x16x32_bf16 v[118:121], v[174:177], v[182:185], v[118:121]
	v_mfma_f32_16x16x32_bf16 v[106:109], v[166:169], v[190:193], v[106:109]
	v_mfma_f32_16x16x32_bf16 v[102:105], v[174:177], v[190:193], v[102:105]
	v_mfma_f32_16x16x32_bf16 v[86:89], v[166:169], v[208:211], v[86:89]
	v_mfma_f32_16x16x32_bf16 v[82:85], v[174:177], v[208:211], v[82:85]
	v_mfma_f32_16x16x32_bf16 v[70:73], v[166:169], v[216:219], v[70:73]
	v_mfma_f32_16x16x32_bf16 v[66:69], v[174:177], v[216:219], v[66:69]
	s_setprio 0
	s_barrier
	s_add_i32 s54, s52, s6
	s_add_i32 m0, s54, 0xffffff80
	ds_read_b128 v[178:181], v145 offset:49152
	ds_read_b128 v[182:185], v145 offset:50176
	ds_read_b128 v[186:189], v145 offset:51200
	ds_read_b128 v[190:193], v145 offset:52224
	ds_read_b128 v[194:197], v145 offset:53248
	ds_read_b128 v[208:211], v145 offset:54272
	ds_read_b128 v[212:215], v145 offset:55296
	ds_read_b128 v[216:219], v145 offset:56320
	global_load_lds_dwordx4 v134, s[40:41] offset:128
	s_add_i32 m0, s54, 0x1f80
	s_nop 0
	global_load_lds_dwordx4 v94, s[40:41] offset:128
	s_add_i32 s54, s53, s6
	s_add_u32 s40, s40, 0x40080
	s_addc_u32 s41, s41, 0
	s_mov_b32 m0, s54
	s_nop 0
	global_load_lds_dwordx4 v134, s[40:41]
	s_add_i32 m0, s54, 0x2000
	s_nop 0
	global_load_lds_dwordx4 v94, s[40:41]
	s_add_u32 s42, s42, 0xfffc0080
	s_addc_u32 s43, s43, -1
	s_mov_b32 m0, s28
	s_nop 0
	global_load_lds_dwordx4 v134, s[42:43]
	s_mov_b32 m0, s29
	s_nop 0
	global_load_lds_dwordx4 v94, s[42:43]
	s_waitcnt vmcnt(8)
	s_waitcnt lgkmcnt(0)
	s_barrier
	s_setprio 1
	s_waitcnt lgkmcnt(0)
	v_mfma_f32_16x16x32_bf16 v[62:65], v[146:149], v[178:181], v[62:65]
	v_mfma_f32_16x16x32_bf16 v[58:61], v[154:157], v[178:181], v[58:61]
	v_mfma_f32_16x16x32_bf16 v[46:49], v[146:149], v[186:189], v[46:49]
	v_mfma_f32_16x16x32_bf16 v[42:45], v[154:157], v[186:189], v[42:45]
	v_mfma_f32_16x16x32_bf16 v[30:33], v[146:149], v[194:197], v[30:33]
	v_mfma_f32_16x16x32_bf16 v[26:29], v[154:157], v[194:197], v[26:29]
	v_mfma_f32_16x16x32_bf16 v[14:17], v[146:149], v[212:215], v[14:17]
	v_mfma_f32_16x16x32_bf16 v[10:13], v[154:157], v[212:215], v[10:13]
	v_mfma_f32_16x16x32_bf16 v[62:65], v[150:153], v[182:185], v[62:65]
	v_mfma_f32_16x16x32_bf16 v[58:61], v[158:161], v[182:185], v[58:61]
	v_mfma_f32_16x16x32_bf16 v[46:49], v[150:153], v[190:193], v[46:49]
	v_mfma_f32_16x16x32_bf16 v[42:45], v[158:161], v[190:193], v[42:45]
	v_mfma_f32_16x16x32_bf16 v[30:33], v[150:153], v[208:211], v[30:33]
	v_mfma_f32_16x16x32_bf16 v[26:29], v[158:161], v[208:211], v[26:29]
	v_mfma_f32_16x16x32_bf16 v[14:17], v[150:153], v[216:219], v[14:17]
	v_mfma_f32_16x16x32_bf16 v[10:13], v[158:161], v[216:219], v[10:13]
	s_setprio 0
	s_setprio 1
	v_mfma_f32_16x16x32_bf16 v[54:57], v[162:165], v[178:181], v[54:57]
	v_mfma_f32_16x16x32_bf16 v[50:53], v[170:173], v[178:181], v[50:53]
	v_mfma_f32_16x16x32_bf16 v[38:41], v[162:165], v[186:189], v[38:41]
	v_mfma_f32_16x16x32_bf16 v[34:37], v[170:173], v[186:189], v[34:37]
	v_mfma_f32_16x16x32_bf16 v[22:25], v[162:165], v[194:197], v[22:25]
	v_mfma_f32_16x16x32_bf16 v[18:21], v[170:173], v[194:197], v[18:21]
	v_mfma_f32_16x16x32_bf16 v[6:9], v[162:165], v[212:215], v[6:9]
	v_mfma_f32_16x16x32_bf16 v[2:5], v[170:173], v[212:215], v[2:5]
	v_mfma_f32_16x16x32_bf16 v[54:57], v[166:169], v[182:185], v[54:57]
	v_mfma_f32_16x16x32_bf16 v[50:53], v[174:177], v[182:185], v[50:53]
	v_mfma_f32_16x16x32_bf16 v[38:41], v[166:169], v[190:193], v[38:41]
	v_mfma_f32_16x16x32_bf16 v[34:37], v[174:177], v[190:193], v[34:37]
	v_mfma_f32_16x16x32_bf16 v[22:25], v[166:169], v[208:211], v[22:25]
	v_mfma_f32_16x16x32_bf16 v[18:21], v[174:177], v[208:211], v[18:21]
	v_mfma_f32_16x16x32_bf16 v[6:9], v[166:169], v[216:219], v[6:9]
	v_mfma_f32_16x16x32_bf16 v[2:5], v[174:177], v[216:219], v[2:5]
	s_setprio 0
	s_barrier
	s_add_i32 s51, s51, 2
	s_add_u32 s49, s49, 0x100
	s_addc_u32 s50, s50, 0
	s_add_u32 s38, s38, 0x100
	s_addc_u32 s39, s39, 0
	s_cmp_gt_u32 s51, 13
	s_cbranch_scc0 .LBB0_565
	s_lshl_b32 s19, s46, 8
	s_add_i32 s19, s19, s25
	v_or_b32_e32 v146, s19, v97
	v_or_b32_e32 v148, 16, v146
	v_or_b32_e32 v150, 32, v146
	v_ashrrev_i32_e32 v149, 31, v148
	v_ashrrev_i32_e32 v151, 31, v150
	v_lshl_add_u64 v[148:149], v[148:149], 4, s[16:17]
	v_lshl_add_u64 v[156:157], v[150:151], 4, s[16:17]
	global_load_dwordx4 v[150:153], v[148:149], off
	s_nop 0
	global_load_dwordx4 v[156:159], v[156:157], off
	v_or_b32_e32 v148, 48, v146
	v_ashrrev_i32_e32 v149, 31, v148
	v_lshl_add_u64 v[160:161], v[148:149], 4, s[16:17]
	v_add_u32_e32 v148, 0x80, v146
	v_ashrrev_i32_e32 v147, 31, v146
	v_ashrrev_i32_e32 v149, 31, v148
	v_lshl_add_u64 v[154:155], v[146:147], 4, s[16:17]
	v_lshl_add_u64 v[146:147], v[148:149], 4, s[16:17]
	global_load_dwordx4 v[160:163], v[160:161], off
	s_nop 0
	global_load_dwordx4 v[164:167], v[146:147], off
	global_load_dwordx4 v[168:171], v[154:155], off
	global_load_dwordx4 v[172:175], v[154:155], off offset:2304
	global_load_dwordx4 v[176:179], v[154:155], off offset:2560
	global_load_dwordx4 v[180:183], v[154:155], off offset:2816
	v_lshl_or_b32 v184, s45, 7, v143
	s_and_b64 vcc, exec, s[10:11]
	s_cbranch_vccz .LBB0_568
	s_barrier
